# W_in round-4 / mixer overlap + drain wait at the skip target (hardening)
# speedup vs baseline: 1.0118x; 1.0015x over previous
.Lwb0_after:
	s_waitcnt vmcnt(0) lgkmcnt(0)
	s_sub_i32 s2, s2, 0x300
	v_readlane_b32 s3, v255, 0
	v_readlane_b32 s10, v255, 1
	v_readlane_b32 s11, v255, 2
	v_readlane_b32 s12, v255, 3
	v_readlane_b32 s13, v255, 4
	v_readlane_b32 s14, v255, 5
	v_readlane_b32 s15, v255, 6
	v_readlane_b32 s16, v255, 7
	v_readlane_b32 s17, v255, 8
	v_readlane_b32 s20, v255, 9
	v_readlane_b32 s21, v255, 10
	v_readlane_b32 s28, v255, 11
	v_readlane_b32 s30, v255, 12
	v_readlane_b32 s34, v255, 13
	v_readlane_b32 s38, v255, 14
	v_readlane_b32 s48, v255, 15
	v_readlane_b32 s49, v255, 16
	v_readlane_b32 s52, v255, 17
	v_readlane_b32 s53, v255, 18
	v_readlane_b32 s54, v255, 19
	v_readlane_b32 s56, v255, 20
	v_readlane_b32 s57, v255, 21
	v_readlane_b32 s69, v255, 22
	v_mov_b32_e32 v0, v176
	s_lshl_b32 s3, s3, 3
	v_readfirstlane_b32 s6, v0
	s_ashr_i32 s7, s6, 6
	s_add_i32 s3, s3, s7
	s_mov_b64 s[8:9], s[0:1]
	s_cmpk_gt_i32 s3, 0x7ff
	s_cbranch_scc1 .LBB0_321
	v_bfe_u32 v3, v0, 4, 2
	s_mulk_i32 s7, 0x4400
	v_lshlrev_b32_e32 v77, 2, v3
	v_and_b32_e32 v1, 63, v0
	s_add_i32 s7, s7, 0
	v_and_b32_e32 v72, 15, v0
	v_and_b32_e32 v0, 48, v0
	v_or_b32_e32 v102, 1, v77
	v_or_b32_e32 v104, 2, v77
	v_or_b32_e32 v106, 3, v77
	v_lshlrev_b32_e32 v2, 9, v3
	v_add_u32_e32 v76, s7, v0
	v_lshl_add_u32 v0, v3, 11, s7
	v_lshlrev_b32_e32 v3, 3, v72
	v_lshl_add_u32 v4, v102, 9, s7
	v_lshl_add_u32 v5, v104, 9, s7
	v_lshl_add_u32 v6, v106, 9, s7
	v_add_u32_e32 v79, v0, v3
	v_add_u32_e32 v103, v4, v3
	v_add_u32_e32 v105, v5, v3
	v_add_u32_e32 v107, v6, v3
	v_or_b32_e32 v7, 0x80, v3
	v_or_b32_e32 v3, 0x100, v3
	s_bfe_u32 s6, s6, 0x20006
	s_lshl_b32 s20, s10, 3
	v_add_u32_e32 v112, v0, v3
	v_add_u32_e32 v113, v4, v3
	v_add_u32_e32 v114, v5, v3
	v_add_u32_e32 v115, v6, v3
	v_or_b32_e32 v3, 48, v1
	s_lshl_b32 s10, s6, 6
	v_lshl_add_u32 v73, v1, 1, s7
	v_add_u32_e32 v108, v0, v7
	v_add_u32_e32 v109, v4, v7
	v_add_u32_e32 v110, v5, v7
	v_add_u32_e32 v111, v6, v7
	v_lshlrev_b32_e32 v7, 3, v3
	v_or_b32_e32 v78, s10, v1
	v_lshl_add_u32 v1, v1, 3, s7
	v_mov_b32_e32 v75, 0
	v_add_u32_e32 v116, v0, v7
	s_lshl_b32 s6, s6, 12
	v_or_b32_e32 v0, s10, v72
	v_add_u32_e32 v122, 0x2400, v1
	v_mov_b32_e32 v1, 0x18000800
	s_mov_b32 s11, 0
	v_add_u32_e32 v117, v4, v7
	v_add_u32_e32 v118, v5, v7
	v_add_u32_e32 v119, v6, v7
	v_lshl_add_u32 v120, v72, 1, s7
	v_lshl_add_u32 v121, v3, 1, s7
	v_lshlrev_b32_e32 v80, 3, v78
	v_mov_b32_e32 v81, v75
	v_lshl_or_b32 v82, v78, 2, v1
	v_mov_b32_e32 v83, v75
	v_mov_b64_e32 v[84:85], s[8:9]
	v_lshlrev_b32_e32 v86, 2, v78
	v_mov_b32_e32 v87, v75
	s_and_b32 s12, s2, 7
	s_lshl_b32 s12, s12, 23
	s_add_u32 s12, s12, 0xd000000
	s_mov_b32 s13, 0
	s_lshl_b32 s10, s6, 2
	v_lshlrev_b32_e32 v88, 2, v2
	v_lshlrev_b32_e32 v90, 2, v72
	s_movk_i32 s21, 0x2000
	s_movk_i32 s22, 0x1000
	s_movk_i32 s23, 0x3000
	s_movk_i32 s26, 0x4000
	s_movk_i32 s27, 0x5000
	s_movk_i32 s28, 0x6000
	s_movk_i32 s29, 0x7000
	s_mov_b32 s30, 0x8000
	s_mov_b32 s31, 0x9000
	s_mov_b32 s34, 0xa000
	s_mov_b32 s35, 0xb000
	s_mov_b32 s36, 0xc000
	s_mov_b32 s37, 0xd000
	s_mov_b32 s38, 0xe000
	s_mov_b32 s39, 0xf000
	s_mov_b32 s42, 0x10000
	s_mov_b32 s43, 0x11000
	s_mov_b32 s44, 0x12000
	s_mov_b32 s45, 0x13000
	s_mov_b32 s50, 0x14000
	s_mov_b32 s51, 0x15000
	s_mov_b32 s52, 0x16000
	s_mov_b32 s53, 0x17000
	s_mov_b32 s54, 0x18000
	s_mov_b32 s55, 0x19000
	s_mov_b32 s56, 0x1a000
	s_mov_b32 s57, 0x1b000
	s_mov_b32 s58, 0x1c000
	s_mov_b32 s59, 0x1d000
	s_mov_b32 s60, 0x1e000
	s_mov_b32 s61, 0x1f000
	s_mov_b32 s62, 0x20000
	s_mov_b32 s63, 0x21000
	s_mov_b32 s64, 0x22000
	s_mov_b32 s65, 0x23000
	s_mov_b32 s66, 0x24000
	s_mov_b32 s67, 0x25000
	s_mov_b32 s70, 0x26000
	s_mov_b32 s71, 0x27000
	s_mov_b32 s72, 0x28000
	s_mov_b32 s73, 0x29000
	s_mov_b32 s74, 0x2a000
	s_mov_b32 s75, 0x2b000
	s_mov_b32 s76, 0x2c000
	s_mov_b32 s77, 0x2d000
	s_mov_b32 s78, 0x2e000
	s_mov_b32 s79, 0x2f000
	s_mov_b32 s80, 0x30000
	s_mov_b32 s81, 0x31000
	s_mov_b32 s82, 0x32000
	s_mov_b32 s83, 0x33000
	s_mov_b32 s84, 0x34000
	s_mov_b32 s85, 0x35000
	s_mov_b32 s86, 0x36000
	s_mov_b32 s87, 0x37000
	v_lshlrev_b32_e32 v92, 2, v0
	s_mov_b32 s88, 0x3f2aaaab
	v_mov_b32_e32 v123, 0x3ecc95a3
	s_mov_b32 s89, 0x3f317218
	s_mov_b32 s90, 0x7f800000
	s_mov_b32 s91, 0x33800000
	s_movk_i32 s92, 0x90
	s_mov_b32 s93, 0xf800000
	v_mov_b32_e32 v124, 0x260
	s_mov_b64 s[14:15], 0x1000
	s_mov_b64 s[16:17], 0x4000
	v_mov_b32_e32 v125, 0xe00
	v_mov_b32_e32 v126, 0x7f800000
	v_mov_b32_e32 v127, 0x7fc00000
	v_mov_b32_e32 v128, 0xff800000

.Lwb1_after:
	s_waitcnt vmcnt(0) lgkmcnt(0)
	s_sub_i32 s2, s2, 0x300
	v_readlane_b32 s3, v255, 0
	v_readlane_b32 s12, v255, 1
	v_readlane_b32 s13, v255, 2
	v_readlane_b32 s14, v255, 3
	v_readlane_b32 s15, v255, 4
	v_readlane_b32 s16, v255, 5
	v_readlane_b32 s17, v255, 6
	v_readlane_b32 s21, v255, 7
	v_readlane_b32 s22, v255, 8
	v_readlane_b32 s23, v255, 9
	v_readlane_b32 s28, v255, 10
	v_readlane_b32 s34, v255, 11
	v_readlane_b32 s50, v255, 12
	v_mov_b32_e32 v0, v176
	s_lshl_b32 s3, s3, 3
	v_readfirstlane_b32 s8, v0
	s_ashr_i32 s9, s8, 6
	s_add_i32 s3, s3, s9
	s_mov_b64 s[10:11], s[0:1]
	s_cmpk_gt_i32 s3, 0x7ff
	s_cbranch_scc1 .LBB0_1058
	v_bfe_u32 v3, v0, 4, 2
	s_mulk_i32 s9, 0x4400
	v_lshlrev_b32_e32 v77, 2, v3
	v_and_b32_e32 v1, 63, v0
	s_add_i32 s9, s9, 0
	v_and_b32_e32 v72, 15, v0
	v_and_b32_e32 v0, 48, v0
	v_or_b32_e32 v102, 1, v77
	v_or_b32_e32 v104, 2, v77
	v_or_b32_e32 v106, 3, v77
	v_lshlrev_b32_e32 v2, 9, v3
	v_add_u32_e32 v76, s9, v0
	v_lshl_add_u32 v0, v3, 11, s9
	v_lshlrev_b32_e32 v3, 3, v72
	v_lshl_add_u32 v4, v102, 9, s9
	v_lshl_add_u32 v5, v104, 9, s9
	v_lshl_add_u32 v6, v106, 9, s9
	v_add_u32_e32 v79, v0, v3
	v_add_u32_e32 v103, v4, v3
	v_add_u32_e32 v105, v5, v3
	v_add_u32_e32 v107, v6, v3
	v_or_b32_e32 v7, 0x80, v3
	v_or_b32_e32 v3, 0x100, v3
	s_bfe_u32 s8, s8, 0x20006
	s_lshl_b32 s26, s12, 3
	v_add_u32_e32 v112, v0, v3
	v_add_u32_e32 v113, v4, v3
	v_add_u32_e32 v114, v5, v3
	v_add_u32_e32 v115, v6, v3
	v_or_b32_e32 v3, 48, v1
	s_lshl_b32 s12, s8, 6
	v_lshl_add_u32 v73, v1, 1, s9
	v_add_u32_e32 v108, v0, v7
	v_add_u32_e32 v109, v4, v7
	v_add_u32_e32 v110, v5, v7
	v_add_u32_e32 v111, v6, v7
	v_lshlrev_b32_e32 v7, 3, v3
	v_or_b32_e32 v78, s12, v1
	v_lshl_add_u32 v1, v1, 3, s9
	v_mov_b32_e32 v75, 0
	v_add_u32_e32 v116, v0, v7
	s_lshl_b32 s8, s8, 12
	v_or_b32_e32 v0, s12, v72
	v_add_u32_e32 v122, 0x2400, v1
	v_mov_b32_e32 v1, 0x18000800
	s_mov_b32 s13, 0
	v_add_u32_e32 v117, v4, v7
	v_add_u32_e32 v118, v5, v7
	v_add_u32_e32 v119, v6, v7
	v_lshl_add_u32 v120, v72, 1, s9
	v_lshl_add_u32 v121, v3, 1, s9
	v_lshlrev_b32_e32 v80, 3, v78
	v_mov_b32_e32 v81, v75
	v_lshl_or_b32 v82, v78, 2, v1
	v_mov_b32_e32 v83, v75
	v_mov_b64_e32 v[84:85], s[10:11]
	v_lshlrev_b32_e32 v86, 2, v78
	v_mov_b32_e32 v87, v75
	s_mov_b64 s[14:15], 0x1000
	s_movk_i32 s27, 0x1000
	s_and_b32 s16, s2, 7
	s_lshl_b32 s16, s16, 23
	s_add_u32 s16, s16, 0xd000000
	s_mov_b32 s17, 0
	s_lshl_b32 s12, s8, 2
	v_lshlrev_b32_e32 v88, 2, v2
	v_lshlrev_b32_e32 v90, 2, v72
	s_mov_b64 s[18:19], 0x10000
	s_mov_b32 s28, 0x10000
	s_mov_b32 s29, 0x12000
	s_movk_i32 s30, 0x2000
	s_movk_i32 s31, 0x3000
	s_movk_i32 s34, 0x4000
	s_movk_i32 s35, 0x5000
	s_movk_i32 s36, 0x6000
	s_movk_i32 s37, 0x7000
	s_mov_b32 s38, 0x8000
	s_mov_b32 s39, 0x9000
	s_mov_b32 s40, 0xa000
	s_mov_b32 s41, 0xb000
	s_mov_b32 s42, 0xc000
	s_mov_b32 s43, 0xd000
	s_mov_b32 s44, 0xe000
	s_mov_b32 s45, 0xf000
	s_mov_b32 s48, 0x11000
	s_mov_b32 s49, 0x13000
	s_mov_b32 s50, 0x14000
	s_mov_b32 s51, 0x15000
	s_mov_b32 s52, 0x16000
	s_mov_b32 s53, 0x17000
	s_mov_b32 s54, 0x18000
	s_mov_b32 s55, 0x19000
	s_mov_b32 s56, 0x1a000
	s_mov_b32 s57, 0x1b000
	s_mov_b32 s58, 0x1c000
	s_mov_b32 s59, 0x1d000
	s_mov_b32 s60, 0x1e000
	s_mov_b32 s61, 0x1f000
	s_mov_b32 s62, 0x20000
	s_mov_b32 s63, 0x21000
	s_mov_b32 s64, 0x22000
	s_mov_b32 s65, 0x23000
	s_mov_b32 s66, 0x24000
	s_mov_b32 s67, 0x25000
	s_mov_b32 s70, 0x26000
	s_mov_b32 s71, 0x27000
	s_mov_b32 s72, 0x28000
	s_mov_b32 s73, 0x29000
	s_mov_b32 s74, 0x2a000
	s_mov_b32 s75, 0x2b000
	s_mov_b32 s76, 0x2c000
	s_mov_b32 s77, 0x2d000
	s_mov_b32 s78, 0x2e000
	s_mov_b32 s79, 0x2f000
	s_mov_b32 s80, 0x30000
	s_mov_b32 s81, 0x31000
	s_mov_b32 s82, 0x32000
	s_mov_b32 s83, 0x33000
	s_mov_b32 s84, 0x34000
	s_mov_b32 s85, 0x35000
	s_mov_b32 s86, 0x36000
	s_mov_b32 s87, 0x37000
	v_lshlrev_b32_e32 v92, 2, v0
	s_mov_b32 s88, 0x3f2aaaab
	v_mov_b32_e32 v123, 0x3ecc95a3
	s_mov_b32 s89, 0x3f317218
	s_mov_b32 s90, 0x7f800000
	s_mov_b32 s91, 0x33800000
	s_movk_i32 s92, 0x90
	s_mov_b32 s93, 0xf800000
	v_mov_b32_e32 v124, 0x260
	s_mov_b64 s[20:21], 0x4000
	v_mov_b32_e32 v125, 0xe00
	v_mov_b32_e32 v126, 0x7f800000
	v_mov_b32_e32 v127, 0x7fc00000
	v_mov_b32_e32 v128, 0xff800000
